# grid barrier: flat release - all workgroups poll the top generation word directly; per-XCD leader no longer re-broadcasts via its XCD generation word
# speedup vs baseline: 1.0131x; 1.0065x over previous
.LBB0_60:
	s_or_b64 exec, exec, s[8:9]
	v_cvt_f32_u32_e32 v4, v2
	s_waitcnt vmcnt(0)
	v_readfirstlane_b32 s3, v3
	v_sub_u32_e32 v3, 0, v2
	v_rcp_iflag_f32_e32 v4, v4
	v_add_u32_e32 v5, s3, v1
	v_mul_f32_e32 v4, 0x4f7ffffe, v4
	v_cvt_u32_f32_e32 v4, v4
	v_mul_lo_u32 v1, v3, v4
	v_mul_hi_u32 v1, v4, v1
	v_add_u32_e32 v1, v4, v1
	v_mul_hi_u32 v1, v5, v1
	v_mul_lo_u32 v3, v1, v2
	v_sub_u32_e32 v3, v5, v3
	v_add_u32_e32 v4, 1, v1
	v_cmp_ge_u32_e32 vcc, v3, v2
	s_nop 1
	v_cndmask_b32_e32 v1, v1, v4, vcc
	v_sub_u32_e32 v4, v3, v2
	v_cndmask_b32_e32 v3, v3, v4, vcc
	v_add_u32_e32 v4, 1, v1
	v_cmp_ge_u32_e32 vcc, v3, v2
	v_add_u32_e32 v3, 1, v5
	s_nop 0
	v_cndmask_b32_e32 v1, v1, v4, vcc
	v_mul_lo_u32 v4, v2, v1
	v_add_u32_e32 v2, v4, v2
	v_cmp_ne_u32_e32 vcc, v3, v2
	s_and_saveexec_b64 s[6:7], vcc
	s_xor_b64 s[6:7], exec, s[6:7]
	s_cbranch_execz .LBB0_74
	s_waitcnt lgkmcnt(0)
	s_add_u32 s12, s24, 0xed25500
	s_addc_u32 s13, s25, 0
	v_mov_b32_e32 v0, 0
	global_load_dword v0, v0, s[12:13] sc1
	s_waitcnt vmcnt(0)
	v_cmp_eq_u32_e32 vcc, v0, v1
	s_and_saveexec_b64 s[8:9], vcc
	s_cbranch_execz .LBB0_73
	s_add_u32 s10, s24, 0xed22200
	s_addc_u32 s11, s25, 0
	s_mov_b32 s3, 1
	s_mov_b64 s[14:15], 0
	v_mov_b32_e32 v0, 0
	s_branch .LBB0_64

.LBB0_91:
	s_or_b64 exec, exec, s[6:7]
	s_mov_b64 s[6:7], exec
	v_mbcnt_lo_u32_b32 v0, s6, 0
	v_mbcnt_hi_u32_b32 v0, s7, v0
	v_cmp_eq_u32_e32 vcc, 0, v0
	s_waitcnt vmcnt(0)
	buffer_inv sc1
	s_and_saveexec_b64 s[8:9], vcc
	s_cbranch_execz .LBB0_93
	s_bcnt1_i32_b64 s3, s[6:7]
	v_mov_b32_e32 v0, 0x2000
	v_mov_b32_e32 v1, s3
.LBB0_93:
	s_or_b64 exec, exec, s[8:9]
	s_waitcnt vmcnt(0)

.LBB0_219:
	s_or_b64 exec, exec, s[8:9]
	s_mov_b64 s[8:9], exec
	v_mbcnt_lo_u32_b32 v0, s8, 0
	v_mbcnt_hi_u32_b32 v0, s9, v0
	v_cmp_eq_u32_e32 vcc, 0, v0
	s_waitcnt vmcnt(0)
	buffer_inv sc1
	s_and_saveexec_b64 s[10:11], vcc
	s_cbranch_execz .LBB0_221
	s_bcnt1_i32_b64 s3, s[8:9]
	v_mov_b32_e32 v0, 0x2000
	v_mov_b32_e32 v1, s3
.LBB0_221:
	s_or_b64 exec, exec, s[10:11]
	s_waitcnt vmcnt(0)

.LBB0_810:
	s_or_b64 exec, exec, s[8:9]
	s_mov_b64 s[8:9], exec
	v_mbcnt_lo_u32_b32 v0, s8, 0
	v_mbcnt_hi_u32_b32 v0, s9, v0
	v_cmp_eq_u32_e32 vcc, 0, v0
	s_waitcnt vmcnt(0)
	buffer_inv sc1
	s_and_saveexec_b64 s[10:11], vcc
	s_cbranch_execz .LBB0_812
	s_bcnt1_i32_b64 s3, s[8:9]
	v_mov_b32_e32 v0, 0x2000
	v_mov_b32_e32 v1, s3
.LBB0_812:
	s_or_b64 exec, exec, s[10:11]
	s_waitcnt vmcnt(0)

.LBB0_954:
	s_or_b64 exec, exec, s[12:13]
	v_cvt_f32_u32_e32 v4, v2
	s_waitcnt vmcnt(0)
	v_readfirstlane_b32 s3, v3
	v_sub_u32_e32 v3, 0, v2
	v_rcp_iflag_f32_e32 v4, v4
	v_add_u32_e32 v5, s3, v1
	v_mul_f32_e32 v4, 0x4f7ffffe, v4
	v_cvt_u32_f32_e32 v4, v4
	v_mul_lo_u32 v1, v3, v4
	v_mul_hi_u32 v1, v4, v1
	v_add_u32_e32 v1, v4, v1
	v_mul_hi_u32 v1, v5, v1
	v_mul_lo_u32 v3, v1, v2
	v_sub_u32_e32 v3, v5, v3
	v_add_u32_e32 v4, 1, v1
	v_cmp_ge_u32_e32 vcc, v3, v2
	s_nop 1
	v_cndmask_b32_e32 v1, v1, v4, vcc
	v_sub_u32_e32 v4, v3, v2
	v_cndmask_b32_e32 v3, v3, v4, vcc
	v_add_u32_e32 v4, 1, v1
	v_cmp_ge_u32_e32 vcc, v3, v2
	v_add_u32_e32 v3, 1, v5
	s_nop 0
	v_cndmask_b32_e32 v1, v1, v4, vcc
	v_mul_lo_u32 v4, v2, v1
	v_add_u32_e32 v2, v4, v2
	v_cmp_ne_u32_e32 vcc, v3, v2
	s_and_saveexec_b64 s[10:11], vcc
	s_xor_b64 s[10:11], exec, s[10:11]
	s_cbranch_execz .LBB0_968
	s_waitcnt lgkmcnt(0)
	s_add_u32 s42, s24, 0xed25500
	s_addc_u32 s43, s25, 0
	v_mov_b32_e32 v0, 0
	global_load_dword v0, v0, s[42:43] sc1
	s_waitcnt vmcnt(0)
	v_cmp_eq_u32_e32 vcc, v0, v1
	s_and_saveexec_b64 s[12:13], vcc
	s_cbranch_execz .LBB0_967
	s_add_u32 s40, s24, 0xed22200
	s_addc_u32 s41, s25, 0
	s_mov_b32 s3, 1
	s_mov_b64 s[46:47], 0
	v_mov_b32_e32 v0, 0
	s_branch .LBB0_958

.LBB0_985:
	s_or_b64 exec, exec, s[12:13]
	s_mov_b64 s[12:13], exec
	v_mbcnt_lo_u32_b32 v0, s12, 0
	v_mbcnt_hi_u32_b32 v0, s13, v0
	v_cmp_eq_u32_e32 vcc, 0, v0
	s_waitcnt vmcnt(0)
	buffer_inv sc1
	s_and_saveexec_b64 s[16:17], vcc
	s_cbranch_execz .LBB0_987
	s_bcnt1_i32_b64 s3, s[12:13]
	v_mov_b32_e32 v0, 0x2000
	v_mov_b32_e32 v1, s3
.LBB0_987:
	s_or_b64 exec, exec, s[16:17]
	s_waitcnt vmcnt(0)

.LBB0_1055:
	s_or_b64 exec, exec, s[12:13]
	s_mov_b64 s[12:13], exec
	v_mbcnt_lo_u32_b32 v0, s12, 0
	v_mbcnt_hi_u32_b32 v0, s13, v0
	v_cmp_eq_u32_e32 vcc, 0, v0
	s_waitcnt vmcnt(0)
	buffer_inv sc1
	s_and_saveexec_b64 s[16:17], vcc
	s_cbranch_execz .LBB0_1057
	s_bcnt1_i32_b64 s3, s[12:13]
	v_mov_b32_e32 v0, 0x2000
	v_mov_b32_e32 v1, s3
.LBB0_1057:
	s_or_b64 exec, exec, s[16:17]
	s_waitcnt vmcnt(0)

.LBB0_1090:
	s_or_b64 exec, exec, s[16:17]
	v_cvt_f32_u32_e32 v4, v2
	s_waitcnt vmcnt(0)
	v_readfirstlane_b32 s3, v3
	v_sub_u32_e32 v3, 0, v2
	v_rcp_iflag_f32_e32 v4, v4
	v_add_u32_e32 v5, s3, v1
	v_mul_f32_e32 v4, 0x4f7ffffe, v4
	v_cvt_u32_f32_e32 v4, v4
	v_mul_lo_u32 v1, v3, v4
	v_mul_hi_u32 v1, v4, v1
	v_add_u32_e32 v1, v4, v1
	v_mul_hi_u32 v1, v5, v1
	v_mul_lo_u32 v3, v1, v2
	v_sub_u32_e32 v3, v5, v3
	v_add_u32_e32 v4, 1, v1
	v_cmp_ge_u32_e32 vcc, v3, v2
	s_nop 1
	v_cndmask_b32_e32 v1, v1, v4, vcc
	v_sub_u32_e32 v4, v3, v2
	v_cndmask_b32_e32 v3, v3, v4, vcc
	v_add_u32_e32 v4, 1, v1
	v_cmp_ge_u32_e32 vcc, v3, v2
	v_add_u32_e32 v3, 1, v5
	s_nop 0
	v_cndmask_b32_e32 v1, v1, v4, vcc
	v_mul_lo_u32 v4, v2, v1
	v_add_u32_e32 v2, v4, v2
	v_cmp_ne_u32_e32 vcc, v3, v2
	s_and_saveexec_b64 s[6:7], vcc
	s_xor_b64 s[6:7], exec, s[6:7]
	s_cbranch_execz .LBB0_1104
	s_waitcnt lgkmcnt(0)
	s_add_u32 s46, s24, 0xed25500
	s_addc_u32 s47, s25, 0
	v_mov_b32_e32 v0, 0
	global_load_dword v0, v0, s[46:47] sc1
	s_waitcnt vmcnt(0)
	v_cmp_eq_u32_e32 vcc, v0, v1
	s_and_saveexec_b64 s[40:41], vcc
	s_cbranch_execz .LBB0_1103
	s_add_u32 s42, s24, 0xed22200
	s_addc_u32 s43, s25, 0
	s_mov_b32 s3, 1
	s_mov_b64 s[48:49], 0
	v_mov_b32_e32 v0, 0
	s_branch .LBB0_1094

.LBB0_1121:
	s_or_b64 exec, exec, s[28:29]
	s_mov_b64 s[16:17], exec
	v_mbcnt_lo_u32_b32 v0, s16, 0
	v_mbcnt_hi_u32_b32 v0, s17, v0
	v_cmp_eq_u32_e32 vcc, 0, v0
	s_waitcnt vmcnt(0)
	buffer_inv sc1
	s_and_saveexec_b64 s[28:29], vcc
	s_cbranch_execz .LBB0_1123
	s_bcnt1_i32_b64 s3, s[16:17]
	v_mov_b32_e32 v0, 0x2000
	v_mov_b32_e32 v1, s3
.LBB0_1123:
	s_or_b64 exec, exec, s[28:29]
	s_waitcnt vmcnt(0)

.LBB0_1220:
	s_or_b64 exec, exec, s[16:17]
	v_cvt_f32_u32_e32 v4, v2
	s_waitcnt vmcnt(0)
	v_readfirstlane_b32 s3, v3
	v_sub_u32_e32 v3, 0, v2
	v_rcp_iflag_f32_e32 v4, v4
	v_add_u32_e32 v5, s3, v1
	v_mul_f32_e32 v4, 0x4f7ffffe, v4
	v_cvt_u32_f32_e32 v4, v4
	v_mul_lo_u32 v1, v3, v4
	v_mul_hi_u32 v1, v4, v1
	v_add_u32_e32 v1, v4, v1
	v_mul_hi_u32 v1, v5, v1
	v_mul_lo_u32 v3, v1, v2
	v_sub_u32_e32 v3, v5, v3
	v_add_u32_e32 v4, 1, v1
	v_cmp_ge_u32_e32 vcc, v3, v2
	s_nop 1
	v_cndmask_b32_e32 v1, v1, v4, vcc
	v_sub_u32_e32 v4, v3, v2
	v_cndmask_b32_e32 v3, v3, v4, vcc
	v_add_u32_e32 v4, 1, v1
	v_cmp_ge_u32_e32 vcc, v3, v2
	v_add_u32_e32 v3, 1, v5
	s_nop 0
	v_cndmask_b32_e32 v1, v1, v4, vcc
	v_mul_lo_u32 v4, v2, v1
	v_add_u32_e32 v2, v4, v2
	v_cmp_ne_u32_e32 vcc, v3, v2
	s_and_saveexec_b64 s[6:7], vcc
	s_xor_b64 s[6:7], exec, s[6:7]
	s_cbranch_execz .LBB0_1234
	s_waitcnt lgkmcnt(0)
	s_add_u32 s40, s24, 0xed25500
	s_addc_u32 s41, s25, 0
	v_mov_b32_e32 v0, 0
	global_load_dword v0, v0, s[40:41] sc1
	s_waitcnt vmcnt(0)
	v_cmp_eq_u32_e32 vcc, v0, v1
	s_and_saveexec_b64 s[36:37], vcc
	s_cbranch_execz .LBB0_1233
	s_add_u32 s38, s24, 0xed22200
	s_addc_u32 s39, s25, 0
	s_mov_b32 s3, 1
	s_mov_b64 s[42:43], 0
	v_mov_b32_e32 v0, 0
	s_branch .LBB0_1224

.LBB0_1251:
	s_or_b64 exec, exec, s[6:7]
	s_mov_b64 s[6:7], exec
	v_mbcnt_lo_u32_b32 v0, s6, 0
	v_mbcnt_hi_u32_b32 v0, s7, v0
	v_cmp_eq_u32_e32 vcc, 0, v0
	s_waitcnt vmcnt(0)
	buffer_inv sc1
	s_and_saveexec_b64 s[16:17], vcc
	s_cbranch_execz .LBB0_1253
	s_bcnt1_i32_b64 s3, s[6:7]
	v_mov_b32_e32 v0, 0x2000
	v_mov_b32_e32 v1, s3
.LBB0_1253:
	s_or_b64 exec, exec, s[16:17]
	s_waitcnt vmcnt(0)

.LBB0_1318:
	s_or_b64 exec, exec, s[14:15]
	v_cvt_f32_u32_e32 v4, v2
	s_waitcnt vmcnt(0)
	v_readfirstlane_b32 s3, v3
	v_sub_u32_e32 v3, 0, v2
	v_rcp_iflag_f32_e32 v4, v4
	v_add_u32_e32 v5, s3, v1
	v_mul_f32_e32 v4, 0x4f7ffffe, v4
	v_cvt_u32_f32_e32 v4, v4
	v_mul_lo_u32 v1, v3, v4
	v_mul_hi_u32 v1, v4, v1
	v_add_u32_e32 v1, v4, v1
	v_mul_hi_u32 v1, v5, v1
	v_mul_lo_u32 v3, v1, v2
	v_sub_u32_e32 v3, v5, v3
	v_add_u32_e32 v4, 1, v1
	v_cmp_ge_u32_e32 vcc, v3, v2
	s_nop 1
	v_cndmask_b32_e32 v1, v1, v4, vcc
	v_sub_u32_e32 v4, v3, v2
	v_cndmask_b32_e32 v3, v3, v4, vcc
	v_add_u32_e32 v4, 1, v1
	v_cmp_ge_u32_e32 vcc, v3, v2
	v_add_u32_e32 v3, 1, v5
	s_nop 0
	v_cndmask_b32_e32 v1, v1, v4, vcc
	v_mul_lo_u32 v4, v2, v1
	v_add_u32_e32 v2, v4, v2
	v_cmp_ne_u32_e32 vcc, v3, v2
	s_and_saveexec_b64 s[6:7], vcc
	s_xor_b64 s[6:7], exec, s[6:7]
	s_cbranch_execz .LBB0_1332
	s_waitcnt lgkmcnt(0)
	s_add_u32 s38, s24, 0xed25500
	s_addc_u32 s39, s25, 0
	v_mov_b32_e32 v0, 0
	global_load_dword v0, v0, s[38:39] sc1
	s_waitcnt vmcnt(0)
	v_cmp_eq_u32_e32 vcc, v0, v1
	s_and_saveexec_b64 s[14:15], vcc
	s_cbranch_execz .LBB0_1331
	s_add_u32 s36, s24, 0xed22200
	s_addc_u32 s37, s25, 0
	s_mov_b32 s3, 1
	s_mov_b64 s[40:41], 0
	v_mov_b32_e32 v0, 0
	s_branch .LBB0_1322

.LBB0_1349:
	s_or_b64 exec, exec, s[14:15]
	s_mov_b64 s[14:15], exec
	v_mbcnt_lo_u32_b32 v0, s14, 0
	v_mbcnt_hi_u32_b32 v0, s15, v0
	v_cmp_eq_u32_e32 vcc, 0, v0
	s_waitcnt vmcnt(0)
	buffer_inv sc1
	s_and_saveexec_b64 s[16:17], vcc
	s_cbranch_execz .LBB0_1351
	s_bcnt1_i32_b64 s3, s[14:15]
	v_mov_b32_e32 v0, 0x2000
	v_mov_b32_e32 v1, s3
.LBB0_1351:
	s_or_b64 exec, exec, s[16:17]
	s_waitcnt vmcnt(0)

.LBB0_1422:
	s_or_b64 exec, exec, s[14:15]
	s_mov_b64 s[14:15], exec
	v_mbcnt_lo_u32_b32 v0, s14, 0
	v_mbcnt_hi_u32_b32 v0, s15, v0
	v_cmp_eq_u32_e32 vcc, 0, v0
	s_waitcnt vmcnt(0)
	buffer_inv sc1
	s_and_saveexec_b64 s[16:17], vcc
	s_cbranch_execz .LBB0_1424
	s_bcnt1_i32_b64 s3, s[14:15]
	v_mov_b32_e32 v0, 0x2000
	v_mov_b32_e32 v1, s3
.LBB0_1424:
	s_or_b64 exec, exec, s[16:17]
	s_waitcnt vmcnt(0)

.LBB0_1488:
	s_or_b64 exec, exec, s[14:15]
	s_mov_b64 s[14:15], exec
	v_mbcnt_lo_u32_b32 v0, s14, 0
	v_mbcnt_hi_u32_b32 v0, s15, v0
	v_cmp_eq_u32_e32 vcc, 0, v0
	s_waitcnt vmcnt(0)
	buffer_inv sc1
	s_and_saveexec_b64 s[16:17], vcc
	s_cbranch_execz .LBB0_1490
	s_bcnt1_i32_b64 s3, s[14:15]
	v_mov_b32_e32 v0, 0x2000
	v_mov_b32_e32 v1, s3
.LBB0_1490:
	s_or_b64 exec, exec, s[16:17]
	s_waitcnt vmcnt(0)

.LBB0_1522:
	s_or_b64 exec, exec, s[8:9]
	v_cvt_f32_u32_e32 v4, v2
	s_waitcnt vmcnt(0)
	v_readfirstlane_b32 s6, v3
	v_sub_u32_e32 v3, 0, v2
	v_rcp_iflag_f32_e32 v4, v4
	v_add_u32_e32 v5, s6, v1
	v_mul_f32_e32 v4, 0x4f7ffffe, v4
	v_cvt_u32_f32_e32 v4, v4
	v_mul_lo_u32 v1, v3, v4
	v_mul_hi_u32 v1, v4, v1
	v_add_u32_e32 v1, v4, v1
	v_mul_hi_u32 v1, v5, v1
	v_mul_lo_u32 v3, v1, v2
	v_sub_u32_e32 v3, v5, v3
	v_add_u32_e32 v4, 1, v1
	v_cmp_ge_u32_e32 vcc, v3, v2
	s_nop 1
	v_cndmask_b32_e32 v1, v1, v4, vcc
	v_sub_u32_e32 v4, v3, v2
	v_cndmask_b32_e32 v3, v3, v4, vcc
	v_add_u32_e32 v4, 1, v1
	v_cmp_ge_u32_e32 vcc, v3, v2
	v_add_u32_e32 v3, 1, v5
	s_nop 0
	v_cndmask_b32_e32 v1, v1, v4, vcc
	v_mul_lo_u32 v4, v2, v1
	v_add_u32_e32 v2, v4, v2
	v_cmp_ne_u32_e32 vcc, v3, v2
	s_and_saveexec_b64 s[6:7], vcc
	s_xor_b64 s[6:7], exec, s[6:7]
	s_cbranch_execz .LBB0_1536
	s_waitcnt lgkmcnt(0)
	s_add_u32 s14, s24, 0xed25500
	s_addc_u32 s15, s25, 0
	v_mov_b32_e32 v0, 0
	global_load_dword v0, v0, s[14:15] sc1
	s_waitcnt vmcnt(0)
	v_cmp_eq_u32_e32 vcc, v0, v1
	s_and_saveexec_b64 s[8:9], vcc
	s_cbranch_execz .LBB0_1535
	s_add_u32 s12, s24, 0xed22200
	s_addc_u32 s13, s25, 0
	s_mov_b32 s19, 1
	s_mov_b64 s[16:17], 0
	v_mov_b32_e32 v0, 0
	s_branch .LBB0_1526

.LBB0_1553:
	s_or_b64 exec, exec, s[6:7]
	s_mov_b64 s[6:7], exec
	v_mbcnt_lo_u32_b32 v0, s6, 0
	v_mbcnt_hi_u32_b32 v0, s7, v0
	v_cmp_eq_u32_e32 vcc, 0, v0
	s_waitcnt vmcnt(0)
	buffer_inv sc1
	s_and_saveexec_b64 s[8:9], vcc
	s_cbranch_execz .LBB0_1555
	s_bcnt1_i32_b64 s6, s[6:7]
	v_mov_b32_e32 v0, 0x2000
	v_mov_b32_e32 v1, s6
.LBB0_1555:
	s_or_b64 exec, exec, s[8:9]
	s_waitcnt vmcnt(0)
